# split (arrive/wait) barrier mixA->mixB: arrive right after conv_prepass, wait before ssm; latency+skew hidden behind mlstm+pool (generic in gridDim, full release/acquire)
# baseline (speedup 1.0000x reference)
; __device__ void phase_mixers_a(const Params& p, int layer) {
;     ...
;   conv_prepass(p, layer);
;   for (int it = blockIdx.x; it < 256; it += G) {
;     const int xcd = it & 7, j = it >> 3, pair = xcd * 8 + (j >> 2);
;     mlstm_item(p, layer, pair >> 3, pair & 7, j & 3);
; __device__ __forceinline__ void xcd_barrier(const XcdBarrier& b) {
;   asm volatile("s_waitcnt vmcnt(0)" ::: "memory");
;   __syncthreads();
.LBB0_171:
	s_or_b64 exec, exec, s[2:3]
	s_waitcnt vmcnt(0)
	s_barrier
	s_mov_b64 s[100:101], exec
	v_readlane_b32 s98, v245, 2
	v_readlane_b32 s99, v245, 3
	s_and_b64 s[98:99], s[100:101], s[98:99]
	s_mov_b64 exec, s[98:99]
	s_cbranch_execz .Lsplit_arr_done
	v_readlane_b32 s98, v245, 20
	v_readlane_b32 s99, v245, 21
	s_add_u32 s98, s98, 0x100
	s_addc_u32 s99, s99, 0
	v_mov_b32_e32 v246, s98
	v_mov_b32_e32 v247, s99
	v_mov_b32_e32 v248, 1
	buffer_wbl2 sc1
	s_waitcnt vmcnt(0)
	global_atomic_add v[246:247], v248, off
.Lsplit_arr_done:
	s_mov_b64 exec, s[100:101]
	v_readlane_b32 s0, v245, 26
	v_readlane_b32 s1, v245, 27
	s_and_b64 vcc, exec, s[0:1]
	v_writelane_b32 v243, s40, 18
	s_nop 1
	v_writelane_b32 v243, s41, 19
	s_cbranch_vccnz .LBB0_259
	s_lshl_b32 s0, s42, 3
	s_mov_b32 s14, s66
	v_writelane_b32 v243, s0, 20
	s_branch .LBB0_174

; __device__ __forceinline__ unsigned xb_ld(unsigned* p) { return __hip_atomic_load(p, __ATOMIC_RELAXED, __HIP_MEMORY_SCOPE_AGENT); }
; __device__ __forceinline__ unsigned xb_add(unsigned* p, unsigned v) { return __hip_atomic_fetch_add(p, v, __ATOMIC_RELAXED, __HIP_MEMORY_SCOPE_AGENT); }
; #define XB_SPIN(cond, bar) do { unsigned _sp = 0; while (cond) { __builtin_amdgcn_s_sleep(1); \
;     if ((++_sp & 255u) == 0u) { if (xb_ld(&(bar)[XB_TMO])) break; if (_sp > XB_SPIN_CAP) { atomicAdd(&(bar)[XB_TMO], 1u); break; } } } } while (0)
; __device__ __forceinline__ void xcd_barrier(const XcdBarrier& b) {
;   asm volatile("s_waitcnt vmcnt(0)" ::: "memory");
;   __syncthreads();
;   if (threadIdx.x == 0) {
;     unsigned* bar = b.bar;
;     unsigned bx = b.x;
;     asm volatile("" : "+s"(bx));
;     __builtin_amdgcn_s_waitcnt(0);
;     unsigned nloc = b.st[0], nx = b.st[1];
;     if (nloc == 0u) { xcd_barrier_complete(bar, bx, nloc, nx); b.st[0] = nloc; b.st[1] = nx; }
;     const unsigned old = xb_add(&bar[XB_XSUB(bx)], 1u);
;     const unsigned gen = old / nloc;
;     if (old + 1u == (gen + 1u) * nloc) {
;       __builtin_amdgcn_fence(__ATOMIC_RELEASE, "agent");
;       asm volatile("s_waitcnt vmcnt(0)" ::: "memory");
;       const unsigned og = xb_add(&bar[XB_TOP], 1u);
;       const unsigned tg = og / nx;
;       if (og + 1u == (tg + 1u) * nx) xb_add(&bar[XB_TOPGEN], 1u);
;       else XB_SPIN(xb_ld(&bar[XB_TOPGEN]) == tg, bar);
;       __builtin_amdgcn_fence(__ATOMIC_ACQUIRE, "agent");
;       xb_add(&bar[XB_XGEN(bx)], 1u);
;       asm volatile("s_waitcnt vmcnt(0)" ::: "memory");
;     } else {
;       XB_SPIN(xb_ld(&bar[XB_XGEN(bx)]) == gen, bar);
;       __builtin_amdgcn_fence(__ATOMIC_ACQUIRE, "agent");
;       asm volatile("s_waitcnt vmcnt(0)" ::: "memory");
;     }
;   }
;   __syncthreads();
.LBB0_260:
	s_waitcnt vmcnt(0)
	s_waitcnt lgkmcnt(0)
	s_barrier
	s_mov_b64 s[2:3], exec
	v_readlane_b32 s0, v245, 2
	v_readlane_b32 s1, v245, 3
	s_and_b64 s[0:1], s[2:3], s[0:1]
	s_mov_b64 exec, s[0:1]
	s_cbranch_execz .LBB0_377
	v_readlane_b32 s0, v245, 20
	v_readlane_b32 s1, v245, 21
	s_add_u32 s0, s0, 0x100
	s_addc_u32 s1, s1, 0
	v_mov_b32_e32 v0, s0
	v_mov_b32_e32 v1, s1
	v_readlane_b32 s4, v243, 17
	v_readlane_b32 s5, v243, 3
	s_add_i32 s4, s4, 1
	s_mul_i32 s4, s4, s5
.Lsplit_spin:
	s_sleep 1
	global_load_dword v2, v[0:1], off sc1
	s_waitcnt vmcnt(0)
	v_readfirstlane_b32 s5, v2
	s_cmp_lt_u32 s5, s4
	s_cbranch_scc1 .Lsplit_spin
	buffer_inv sc1
	s_waitcnt vmcnt(0)
	s_branch .LBB0_377

; #define LAS __attribute__((address_space(3)))
; __global__ void __launch_bounds__(512) fwd_megakernel(Params p) {
;   cg::grid_group grid = cg::this_grid();
;   volatile LAS unsigned* st = (volatile LAS unsigned*)((LAS unsigned char*)smem + (DYN_LDS - 16));
;   if (threadIdx.x == 0) { st[0] = 0u; st[1] = 0u; }
;   __syncthreads();
;   const XcdBarrier xb = xcd_barrier_post((unsigned*)(ws_of(p) + OFF_BAR), st);
;   phase_convert(p);
;   if (p.ws == nullptr) grid.sync();
;   xcd_barrier(xb);
; #pragma unroll 1
;   for (int layer = 0; layer < 2; ++layer) {
;     phase_proj(p, layer);
;     xcd_barrier(xb);
;     phase_mixers_a(p, layer);
;     xcd_barrier(xb);
;     phase_mixers_b(p, layer);
;     xcd_barrier(xb);
;     phase_post(p, layer);
;     xcd_barrier(xb);
;     phase_branch(p, layer);
;     xcd_barrier(xb);
;     phase_out(p, layer);
;     xcd_barrier(xb);
;     phase_ln(p, layer);
;     if (layer == 0) xcd_barrier(xb);
;   }
; }
	.amdhsa_kernel _Z14fwd_megakernel6Params
		.amdhsa_group_segment_fixed_size 0
		.amdhsa_private_segment_fixed_size 0
		.amdhsa_kernarg_size 416
		.amdhsa_user_sgpr_count 2
		.amdhsa_user_sgpr_dispatch_ptr 0
		.amdhsa_user_sgpr_queue_ptr 0
		.amdhsa_user_sgpr_kernarg_segment_ptr 1
		.amdhsa_user_sgpr_dispatch_id 0
		.amdhsa_user_sgpr_kernarg_preload_length 0
		.amdhsa_user_sgpr_kernarg_preload_offset 0
		.amdhsa_user_sgpr_private_segment_size 0
		.amdhsa_uses_dynamic_stack 0
		.amdhsa_enable_private_segment 0
		.amdhsa_system_sgpr_workgroup_id_x 1
		.amdhsa_system_sgpr_workgroup_id_y 0
		.amdhsa_system_sgpr_workgroup_id_z 0
		.amdhsa_system_sgpr_workgroup_info 0
		.amdhsa_system_vgpr_workitem_id 2
		.amdhsa_next_free_vgpr 250
		.amdhsa_next_free_sgpr 102
		.amdhsa_accum_offset 252
		.amdhsa_reserve_vcc 1
		.amdhsa_float_round_mode_32 0
		.amdhsa_float_round_mode_16_64 0
		.amdhsa_float_denorm_mode_32 3
		.amdhsa_float_denorm_mode_16_64 3
		.amdhsa_dx10_clamp 1
		.amdhsa_ieee_mode 1
		.amdhsa_fp16_overflow 0
		.amdhsa_tg_split 0
		.amdhsa_exception_fp_ieee_invalid_op 0
		.amdhsa_exception_fp_denorm_src 0
		.amdhsa_exception_fp_ieee_div_zero 0
		.amdhsa_exception_fp_ieee_overflow 0
		.amdhsa_exception_fp_ieee_underflow 0
		.amdhsa_exception_fp_ieee_inexact 0
		.amdhsa_exception_int_div_zero 0
	.end_amdhsa_kernel

; #define LAS __attribute__((address_space(3)))
; __global__ void __launch_bounds__(512) fwd_megakernel(Params p) {
;   cg::grid_group grid = cg::this_grid();
;   volatile LAS unsigned* st = (volatile LAS unsigned*)((LAS unsigned char*)smem + (DYN_LDS - 16));
;   if (threadIdx.x == 0) { st[0] = 0u; st[1] = 0u; }
;   __syncthreads();
;   const XcdBarrier xb = xcd_barrier_post((unsigned*)(ws_of(p) + OFF_BAR), st);
;   phase_convert(p);
;   if (p.ws == nullptr) grid.sync();
;   xcd_barrier(xb);
; #pragma unroll 1
;   for (int layer = 0; layer < 2; ++layer) {
;     phase_proj(p, layer);
;     xcd_barrier(xb);
;     phase_mixers_a(p, layer);
;     xcd_barrier(xb);
;     phase_mixers_b(p, layer);
;     xcd_barrier(xb);
;     phase_post(p, layer);
;     xcd_barrier(xb);
;     phase_branch(p, layer);
;     xcd_barrier(xb);
;     phase_out(p, layer);
;     xcd_barrier(xb);
;     phase_ln(p, layer);
;     if (layer == 0) xcd_barrier(xb);
;   }
; }
amdhsa.kernels:
  - .agpr_count:     0
    .args:
      - .offset:         0
        .size:           160
        .value_kind:     by_value
      - .offset:         160
        .size:           4
        .value_kind:     hidden_block_count_x
      - .offset:         164
        .size:           4
        .value_kind:     hidden_block_count_y
      - .offset:         168
        .size:           4
        .value_kind:     hidden_block_count_z
      - .offset:         172
        .size:           2
        .value_kind:     hidden_group_size_x
      - .offset:         174
        .size:           2
        .value_kind:     hidden_group_size_y
      - .offset:         176
        .size:           2
        .value_kind:     hidden_group_size_z
      - .offset:         178
        .size:           2
        .value_kind:     hidden_remainder_x
      - .offset:         180
        .size:           2
        .value_kind:     hidden_remainder_y
      - .offset:         182
        .size:           2
        .value_kind:     hidden_remainder_z
      - .offset:         200
        .size:           8
        .value_kind:     hidden_global_offset_x
      - .offset:         208
        .size:           8
        .value_kind:     hidden_global_offset_y
      - .offset:         216
        .size:           8
        .value_kind:     hidden_global_offset_z
      - .offset:         224
        .size:           2
        .value_kind:     hidden_grid_dims
      - .offset:         248
        .size:           8
        .value_kind:     hidden_multigrid_sync_arg
      - .offset:         280
        .size:           4
        .value_kind:     hidden_dynamic_lds_size
    .group_segment_fixed_size: 0
    .kernarg_segment_align: 8
    .kernarg_segment_size: 416
    .language:       OpenCL C
    .language_version:
      - 2
      - 0
    .max_flat_workgroup_size: 512
    .name:           _Z14fwd_megakernel6Params
    .private_segment_fixed_size: 0
    .sgpr_count:     108
    .sgpr_spill_count: 156
    .symbol:         _Z14fwd_megakernel6Params.kd
    .uniform_work_group_size: 1
    .uses_dynamic_stack: false
    .vgpr_count:     250
    .vgpr_spill_count: 0
    .wavefront_size: 64
